# v74 + P1 transposer loop publishes each w_in^T block one block later (store acknowledgements get a whole extra block to hide behind)
# speedup vs baseline: 1.0030x; 1.0004x over previous
; #define LAS __attribute__((address_space(3)))
; #define LDS_WAIT() asm volatile("s_waitcnt lgkmcnt(0)" ::: "memory")
; __device__ __forceinline__ unsigned pk2(float lo, float hi) { return (unsigned)f2bf(lo) | ((unsigned)f2bf(hi) << 16); }
; __device__ __forceinline__ unsigned xb_add(unsigned* p, unsigned v) { return __hip_atomic_fetch_add(p, v, __ATOMIC_RELAXED, __HIP_MEMORY_SCOPE_AGENT); }
; __device__ __forceinline__ void p0_item_load(const P0Item& d, f32x4 (&v)[8], int lane) {
; #pragma unroll
;     for (int i = 0; i < 8; ++i) v[i] = __builtin_nontemporal_load((const f32x4*)(d.src + (size_t)(8 * i + (lane >> 3)) * d.N + 4 * (lane & 7)));
; }
; template <bool WT = false>
; __device__ __forceinline__ void p0_item_finish(const P0Item& d, const f32x4 (&v)[8], LAS float* scr, int lane) {
; #pragma unroll
;     for (int i = 0; i < 8; ++i) { LAS float* q = scr + (8 * i + (lane >> 3)) * 33 + 4 * (lane & 7); q[0] = v[i][0]; q[1] = v[i][1]; q[2] = v[i][2]; q[3] = v[i][3]; }
;     LDS_WAIT(); asm volatile("" ::: "memory");
;     const int c = lane & 7;
; #pragma unroll
;     for (int j = 0; j < 4; ++j) { const int n = (lane >> 3) + 8 * j; const LAS float* s = scr + (8 * c) * 33 + n;
;         v4u o; o.x = pk2(s[0 * 33], s[1 * 33]); o.y = pk2(s[2 * 33], s[3 * 33]); o.z = pk2(s[4 * 33], s[5 * 33]); o.w = pk2(s[6 * 33], s[7 * 33]);
;         if constexpr (WT) __builtin_amdgcn_raw_buffer_store_b128(o, __builtin_amdgcn_make_buffer_rsrc((void*)d.dst, 0, 0x7fffffff, 0x00020000), (int)(((size_t)n * d.ldt + 8 * c) * 2), 0, 16);
;         else *(v4u*)(d.dst + (size_t)n * d.ldt + 8 * c) = o; }
;     LDS_WAIT(); asm volatile("" ::: "memory");
; }
; __device__ __forceinline__ void tr_blocks(Frame& F, const Args& a, int T, int b_lo, int b_hi, bool tail) {
;     ...
;         db = p0_item_in(a, T, 8 * (b + 1) + w); p0_item_load(db, vb, F.lane);
;         p0_item_finish<true>(da, va, scr, F.lane);
;         if (b > b_lo) { asm volatile("s_waitcnt vmcnt(12)" ::: "memory"); __syncthreads(); if (F.tid == 0) (void)xb_add(blk + 16 * (b - 1), 1u); }
.LBB0_394:
	s_ashr_i32 s39, s38, 31
	s_lshl_b64 s[38:39], s[38:39], 2
	s_add_u32 s38, s0, s38
	s_addc_u32 s39, s1, s39
	v_lshl_add_u64 v[34:35], s[38:39], 0, v[70:71]
	v_lshl_add_u64 v[36:37], s[38:39], 0, v[72:73]
	v_lshl_add_u64 v[42:43], s[38:39], 0, v[74:75]
	v_lshl_add_u64 v[44:45], s[38:39], 0, v[76:77]
	v_lshl_add_u64 v[50:51], s[38:39], 0, v[78:79]
	v_lshl_add_u64 v[52:53], s[38:39], 0, v[80:81]
	v_lshl_add_u64 v[58:59], s[38:39], 0, v[82:83]
	v_lshl_add_u64 v[60:61], s[38:39], 0, v[84:85]
	v_lshl_add_u64 v[34:35], v[34:35], 0, v[66:67]
	v_lshl_add_u64 v[36:37], v[36:37], 0, v[66:67]
	v_lshl_add_u64 v[42:43], v[42:43], 0, v[66:67]
	v_lshl_add_u64 v[44:45], v[44:45], 0, v[66:67]
	v_lshl_add_u64 v[50:51], v[50:51], 0, v[66:67]
	v_lshl_add_u64 v[52:53], v[52:53], 0, v[66:67]
	v_lshl_add_u64 v[58:59], v[58:59], 0, v[66:67]
	v_lshl_add_u64 v[60:61], v[60:61], 0, v[66:67]
	global_load_dwordx4 v[38:41], v[34:35], off nt
	s_nop 0
	global_load_dwordx4 v[34:37], v[36:37], off nt
	s_nop 0
	global_load_dwordx4 v[46:49], v[42:43], off nt
	s_nop 0
	global_load_dwordx4 v[42:45], v[44:45], off nt
	s_nop 0
	global_load_dwordx4 v[54:57], v[50:51], off nt
	s_nop 0
	global_load_dwordx4 v[50:53], v[52:53], off nt
	s_nop 0
	global_load_dwordx4 v[62:65], v[58:59], off nt
	s_nop 0
	global_load_dwordx4 v[58:61], v[60:61], off nt
	v_add_u32_e32 v98, 0x420, v93
	v_add_u32_e32 v99, 0x428, v93
	v_add_u32_e32 v100, 0x840, v93
	v_add_u32_e32 v101, 0x848, v93
	v_add_u32_e32 v102, 0xc60, v93
	v_add_u32_e32 v103, 0xc68, v93
	v_add_u32_e32 v104, 0x1080, v93
	v_add_u32_e32 v105, 0x1088, v93
	v_add_u32_e32 v106, 0x14a0, v93
	v_add_u32_e32 v107, 0x14a8, v93
	v_add_u32_e32 v108, 0x18c0, v93
	v_add_u32_e32 v109, 0x18c8, v93
	v_add_u32_e32 v110, 0x1ce0, v93
	v_add_u32_e32 v111, 0x1ce8, v93
	s_waitcnt vmcnt(15)
	ds_write2_b32 v93, v6, v7 offset1:1
	ds_write2_b32 v93, v8, v9 offset0:2 offset1:3
	s_waitcnt vmcnt(14)
	ds_write2_b32 v98, v2, v3 offset1:1
	ds_write2_b32 v99, v4, v5 offset1:1
	s_waitcnt vmcnt(13)
	ds_write2_b32 v100, v14, v15 offset1:1
	ds_write2_b32 v101, v16, v17 offset1:1
	s_waitcnt vmcnt(12)
	ds_write2_b32 v102, v10, v11 offset1:1
	ds_write2_b32 v103, v12, v13 offset1:1
	s_waitcnt vmcnt(11)
	ds_write2_b32 v104, v22, v23 offset1:1
	ds_write2_b32 v105, v24, v25 offset1:1
	s_waitcnt vmcnt(10)
	ds_write2_b32 v106, v18, v19 offset1:1
	ds_write2_b32 v107, v20, v21 offset1:1
	s_waitcnt vmcnt(9)
	ds_write2_b32 v108, v30, v31 offset1:1
	ds_write2_b32 v109, v32, v33 offset1:1
	s_waitcnt vmcnt(8)
	ds_write2_b32 v110, v26, v27 offset1:1
	ds_write2_b32 v111, v28, v29 offset1:1
	s_waitcnt lgkmcnt(0)
	ds_read2_b32 v[6:7], v92 offset1:8
	ds_read2_b32 v[8:9], v92 offset0:33 offset1:41
	ds_read2_b32 v[10:11], v92 offset0:66 offset1:74
	ds_read2_b32 v[12:13], v92 offset0:99 offset1:107
	ds_read2_b32 v[14:15], v92 offset0:132 offset1:140
	s_waitcnt lgkmcnt(4)
	s_waitcnt lgkmcnt(3)
	ds_read2_b32 v[16:17], v92 offset0:165 offset1:173
	v_cvt_pk_bf16_f32 v2, v6, v8
	s_waitcnt lgkmcnt(3)
	s_waitcnt lgkmcnt(2)
	ds_read2_b32 v[18:19], v92 offset0:198 offset1:206
	ds_read2_b32 v[20:21], v92 offset0:231 offset1:239
	v_cvt_pk_bf16_f32 v3, v10, v12
	s_waitcnt lgkmcnt(3)
	s_waitcnt lgkmcnt(2)
	v_cvt_pk_bf16_f32 v4, v14, v16
	s_waitcnt lgkmcnt(1)
	s_waitcnt lgkmcnt(0)
	s_and_b32 s5, s5, 0xffff
	v_cvt_pk_bf16_f32 v5, v18, v20
	buffer_store_dwordx4 v[2:5], v97, s[4:7], 0 offen sc1
	s_nop 1
	v_cvt_pk_bf16_f32 v2, v7, v9
	v_cvt_pk_bf16_f32 v3, v11, v13
	v_cvt_pk_bf16_f32 v4, v15, v17
	ds_read2_b32 v[6:7], v92 offset0:16 offset1:24
	v_cvt_pk_bf16_f32 v5, v19, v21
	ds_read2_b32 v[8:9], v92 offset0:49 offset1:57
	ds_read2_b32 v[10:11], v92 offset0:82 offset1:90
	ds_read2_b32 v[12:13], v92 offset0:115 offset1:123
	buffer_store_dwordx4 v[2:5], v96, s[4:7], 0 offen sc1
	s_nop 1
	ds_read2_b32 v[14:15], v92 offset0:148 offset1:156
	ds_read2_b32 v[16:17], v92 offset0:181 offset1:189
	s_waitcnt lgkmcnt(5)
	s_waitcnt lgkmcnt(4)
	v_cvt_pk_bf16_f32 v2, v6, v8
	s_waitcnt lgkmcnt(3)
	s_waitcnt lgkmcnt(2)
	ds_read2_b32 v[18:19], v92 offset0:214 offset1:222
	ds_read2_b32 v[20:21], v92 offset0:247 offset1:255
	v_cvt_pk_bf16_f32 v3, v10, v12
	s_waitcnt lgkmcnt(3)
	s_waitcnt lgkmcnt(2)
	v_cvt_pk_bf16_f32 v4, v14, v16
	s_waitcnt lgkmcnt(1)
	s_waitcnt lgkmcnt(0)
	v_cvt_pk_bf16_f32 v5, v18, v20
	buffer_store_dwordx4 v[2:5], v95, s[4:7], 0 offen sc1
	s_nop 1
	v_cvt_pk_bf16_f32 v2, v7, v9
	v_cvt_pk_bf16_f32 v3, v11, v13
	v_cvt_pk_bf16_f32 v4, v15, v17
	v_cvt_pk_bf16_f32 v5, v19, v21
	buffer_store_dwordx4 v[2:5], v94, s[4:7], 0 offen sc1
	s_nop 1
	s_waitcnt lgkmcnt(0)
	s_cmp_lt_u32 s10, 9
	s_cbranch_scc1 .LBB0_399
	s_waitcnt vmcnt(24)
	s_barrier
	s_and_saveexec_b64 s[4:5], s[2:3]
	s_cbranch_execz .LBB0_398
	s_mov_b64 s[38:39], exec
	v_mbcnt_lo_u32_b32 v2, s38, 0
	v_mbcnt_hi_u32_b32 v2, s39, v2
	v_cmp_eq_u32_e32 vcc, 0, v2
	s_and_b64 s[40:41], exec, vcc
	s_mov_b64 exec, s[40:41]
	s_cbranch_execz .LBB0_398
	s_bcnt1_i32_b64 s28, s[38:39]
	v_mov_b32_e32 v2, s28
	global_atomic_add v67, v2, s[30:31] offset:-64

; #define LAS __attribute__((address_space(3)))
; #define LDS_WAIT() asm volatile("s_waitcnt lgkmcnt(0)" ::: "memory")
; __device__ __forceinline__ unsigned pk2(float lo, float hi) { return (unsigned)f2bf(lo) | ((unsigned)f2bf(hi) << 16); }
; __device__ __forceinline__ unsigned xb_add(unsigned* p, unsigned v) { return __hip_atomic_fetch_add(p, v, __ATOMIC_RELAXED, __HIP_MEMORY_SCOPE_AGENT); }
; __device__ __forceinline__ void p0_item_load(const P0Item& d, f32x4 (&v)[8], int lane) {
; #pragma unroll
;     for (int i = 0; i < 8; ++i) v[i] = __builtin_nontemporal_load((const f32x4*)(d.src + (size_t)(8 * i + (lane >> 3)) * d.N + 4 * (lane & 7)));
; }
; template <bool WT = false>
; __device__ __forceinline__ void p0_item_finish(const P0Item& d, const f32x4 (&v)[8], LAS float* scr, int lane) {
; #pragma unroll
;     for (int i = 0; i < 8; ++i) { LAS float* q = scr + (8 * i + (lane >> 3)) * 33 + 4 * (lane & 7); q[0] = v[i][0]; q[1] = v[i][1]; q[2] = v[i][2]; q[3] = v[i][3]; }
;     LDS_WAIT(); asm volatile("" ::: "memory");
;     const int c = lane & 7;
; #pragma unroll
;     for (int j = 0; j < 4; ++j) { const int n = (lane >> 3) + 8 * j; const LAS float* s = scr + (8 * c) * 33 + n;
;         v4u o; o.x = pk2(s[0 * 33], s[1 * 33]); o.y = pk2(s[2 * 33], s[3 * 33]); o.z = pk2(s[4 * 33], s[5 * 33]); o.w = pk2(s[6 * 33], s[7 * 33]);
;         if constexpr (WT) __builtin_amdgcn_raw_buffer_store_b128(o, __builtin_amdgcn_make_buffer_rsrc((void*)d.dst, 0, 0x7fffffff, 0x00020000), (int)(((size_t)n * d.ldt + 8 * c) * 2), 0, 16);
;         else *(v4u*)(d.dst + (size_t)n * d.ldt + 8 * c) = o; }
;     LDS_WAIT(); asm volatile("" ::: "memory");
; }
; __device__ __forceinline__ void tr_blocks(Frame& F, const Args& a, int T, int b_lo, int b_hi, bool tail) {
;     ...
;         da = p0_item_in(a, T, b + 2 < b_hi ? 8 * (b + 2) + w : (tail ? 448 : 8 * b + w)); p0_item_load(da, va, F.lane);
;         p0_item_finish<true>(db, vb, scr, F.lane);
;         asm volatile("s_waitcnt vmcnt(12)" ::: "memory"); __syncthreads(); if (F.tid == 0) (void)xb_add(blk + 16 * b, 1u);
.LBB0_404:
	s_ashr_i32 s5, s4, 31
	s_lshl_b64 s[4:5], s[4:5], 2
	s_add_u32 s4, s0, s4
	s_addc_u32 s5, s1, s5
	v_lshl_add_u64 v[2:3], s[4:5], 0, v[70:71]
	v_lshl_add_u64 v[4:5], s[4:5], 0, v[72:73]
	v_lshl_add_u64 v[10:11], s[4:5], 0, v[74:75]
	v_lshl_add_u64 v[12:13], s[4:5], 0, v[76:77]
	v_lshl_add_u64 v[18:19], s[4:5], 0, v[78:79]
	v_lshl_add_u64 v[20:21], s[4:5], 0, v[80:81]
	v_lshl_add_u64 v[26:27], s[4:5], 0, v[82:83]
	v_lshl_add_u64 v[28:29], s[4:5], 0, v[84:85]
	v_lshl_add_u64 v[2:3], v[2:3], 0, v[66:67]
	v_lshl_add_u64 v[4:5], v[4:5], 0, v[66:67]
	v_lshl_add_u64 v[10:11], v[10:11], 0, v[66:67]
	v_lshl_add_u64 v[12:13], v[12:13], 0, v[66:67]
	v_lshl_add_u64 v[18:19], v[18:19], 0, v[66:67]
	v_lshl_add_u64 v[20:21], v[20:21], 0, v[66:67]
	v_lshl_add_u64 v[26:27], v[26:27], 0, v[66:67]
	v_lshl_add_u64 v[28:29], v[28:29], 0, v[66:67]
	global_load_dwordx4 v[6:9], v[2:3], off nt
	s_nop 0
	global_load_dwordx4 v[2:5], v[4:5], off nt
	s_nop 0
	global_load_dwordx4 v[14:17], v[10:11], off nt
	s_nop 0
	global_load_dwordx4 v[10:13], v[12:13], off nt
	s_nop 0
	global_load_dwordx4 v[22:25], v[18:19], off nt
	s_nop 0
	global_load_dwordx4 v[18:21], v[20:21], off nt
	s_nop 0
	global_load_dwordx4 v[30:33], v[26:27], off nt
	s_nop 0
	global_load_dwordx4 v[26:29], v[28:29], off nt
	s_waitcnt vmcnt(19)
	ds_write2_b32 v93, v38, v39 offset1:1
	ds_write2_b32 v93, v40, v41 offset0:2 offset1:3
	s_waitcnt vmcnt(18)
	ds_write2_b32 v98, v34, v35 offset1:1
	ds_write2_b32 v99, v36, v37 offset1:1
	s_waitcnt vmcnt(17)
	ds_write2_b32 v100, v46, v47 offset1:1
	ds_write2_b32 v101, v48, v49 offset1:1
	s_waitcnt vmcnt(16)
	ds_write2_b32 v102, v42, v43 offset1:1
	ds_write2_b32 v103, v44, v45 offset1:1
	s_waitcnt vmcnt(15)
	ds_write2_b32 v104, v54, v55 offset1:1
	ds_write2_b32 v105, v56, v57 offset1:1
	s_waitcnt vmcnt(14)
	ds_write2_b32 v106, v50, v51 offset1:1
	ds_write2_b32 v107, v52, v53 offset1:1
	s_waitcnt vmcnt(13)
	ds_write2_b32 v108, v62, v63 offset1:1
	ds_write2_b32 v109, v64, v65 offset1:1
	s_waitcnt vmcnt(12)
	ds_write2_b32 v110, v58, v59 offset1:1
	ds_write2_b32 v111, v60, v61 offset1:1
	s_waitcnt lgkmcnt(0)
	ds_read2_b32 v[38:39], v92 offset1:8
	ds_read2_b32 v[40:41], v92 offset0:33 offset1:41
	ds_read2_b32 v[42:43], v92 offset0:66 offset1:74
	ds_read2_b32 v[44:45], v92 offset0:99 offset1:107
	ds_read2_b32 v[46:47], v92 offset0:132 offset1:140
	s_waitcnt lgkmcnt(4)
	s_waitcnt lgkmcnt(3)
	ds_read2_b32 v[48:49], v92 offset0:165 offset1:173
	v_cvt_pk_bf16_f32 v34, v38, v40
	s_waitcnt lgkmcnt(3)
	s_waitcnt lgkmcnt(2)
	ds_read2_b32 v[50:51], v92 offset0:198 offset1:206
	ds_read2_b32 v[52:53], v92 offset0:231 offset1:239
	v_cvt_pk_bf16_f32 v35, v42, v44
	s_waitcnt lgkmcnt(3)
	s_waitcnt lgkmcnt(2)
	v_cvt_pk_bf16_f32 v36, v46, v48
	s_waitcnt lgkmcnt(1)
	s_waitcnt lgkmcnt(0)
	s_and_b32 s5, s54, 0xffff
	s_mov_b32 s4, s53
	v_cvt_pk_bf16_f32 v37, v50, v52
	buffer_store_dwordx4 v[34:37], v97, s[4:7], 0 offen sc1
	s_nop 1
	v_cvt_pk_bf16_f32 v34, v39, v41
	v_cvt_pk_bf16_f32 v35, v43, v45
	v_cvt_pk_bf16_f32 v36, v47, v49
	ds_read2_b32 v[38:39], v92 offset0:16 offset1:24
	v_cvt_pk_bf16_f32 v37, v51, v53
	ds_read2_b32 v[40:41], v92 offset0:49 offset1:57
	ds_read2_b32 v[42:43], v92 offset0:82 offset1:90
	ds_read2_b32 v[44:45], v92 offset0:115 offset1:123
	buffer_store_dwordx4 v[34:37], v96, s[4:7], 0 offen sc1
	s_nop 1
	ds_read2_b32 v[46:47], v92 offset0:148 offset1:156
	ds_read2_b32 v[48:49], v92 offset0:181 offset1:189
	s_waitcnt lgkmcnt(5)
	s_waitcnt lgkmcnt(4)
	v_cvt_pk_bf16_f32 v34, v38, v40
	s_waitcnt lgkmcnt(3)
	s_waitcnt lgkmcnt(2)
	ds_read2_b32 v[50:51], v92 offset0:214 offset1:222
	ds_read2_b32 v[52:53], v92 offset0:247 offset1:255
	v_cvt_pk_bf16_f32 v35, v42, v44
	s_waitcnt lgkmcnt(3)
	s_waitcnt lgkmcnt(2)
	v_cvt_pk_bf16_f32 v36, v46, v48
	s_waitcnt lgkmcnt(1)
	s_waitcnt lgkmcnt(0)
	v_cvt_pk_bf16_f32 v37, v50, v52
	buffer_store_dwordx4 v[34:37], v95, s[4:7], 0 offen sc1
	s_nop 1
	v_cvt_pk_bf16_f32 v34, v39, v41
	v_cvt_pk_bf16_f32 v35, v43, v45
	v_cvt_pk_bf16_f32 v36, v47, v49
	v_cvt_pk_bf16_f32 v37, v51, v53
	buffer_store_dwordx4 v[34:37], v94, s[4:7], 0 offen sc1
	s_nop 1
	s_waitcnt lgkmcnt(0)
	s_waitcnt vmcnt(24)
	s_barrier
	s_and_saveexec_b64 s[4:5], s[2:3]
	s_cbranch_execz .LBB0_388
	s_cmp_lt_u32 s10, 9
	s_cbranch_scc1 .LBB0_388
	s_mov_b64 s[40:41], exec
	v_mbcnt_lo_u32_b32 v34, s40, 0
	v_mbcnt_hi_u32_b32 v34, s41, v34
	v_cmp_eq_u32_e32 vcc, 0, v34
	s_and_b64 s[58:59], exec, vcc
	s_mov_b64 exec, s[58:59]
	s_cbranch_execz .LBB0_388
	s_bcnt1_i32_b64 s40, s[40:41]
	v_mov_b32_e32 v34, s40
	global_atomic_add v67, v34, s[30:31]
	s_branch .LBB0_388

; __device__ __forceinline__ unsigned xb_add(unsigned* p, unsigned v) { return __hip_atomic_fetch_add(p, v, __ATOMIC_RELAXED, __HIP_MEMORY_SCOPE_AGENT); }
; __device__ __forceinline__ void tr_blocks(Frame& F, const Args& a, int T, int b_lo, int b_hi, bool tail) {
;     ...
;     if (tail && w == 0) p0_item_finish<true>(da, va, scr, F.lane);
;     asm volatile("s_waitcnt vmcnt(0)" ::: "memory"); __syncthreads();
;     if (F.tid == 0) { (void)xb_add(blk + 16 * (b_hi - 1), 1u); if (tail) (void)xb_add(blk + 16 * 56, 1u); }
.LBB0_409:
	s_waitcnt vmcnt(0)
	s_barrier
	s_and_saveexec_b64 s[4:5], s[2:3]
	s_cbranch_execz .LBB0_430
	s_mov_b64 s[6:7], exec
	s_waitcnt vmcnt(10)
	v_mbcnt_lo_u32_b32 v2, s6, 0
	s_add_u32 s2, s26, 0x30dc0
	v_mbcnt_hi_u32_b32 v2, s7, v2
	s_addc_u32 s3, s27, 0
	v_cmp_eq_u32_e32 vcc, 0, v2
	s_and_saveexec_b64 s[28:29], vcc
	s_cbranch_execz .LBB0_412
	s_bcnt1_i32_b64 s0, s[6:7]
	v_mov_b32_e32 v2, 0
	v_mov_b32_e32 v3, s0
	global_atomic_add v2, v3, s[2:3]
	global_atomic_add v2, v3, s[2:3] offset:-64
